# scan: L2 warm-up of the chunk after next issued by the even half of each XCD pair only
# baseline (speedup 1.0000x reference)
.LBB0_159:
	s_and_b64 vcc, exec, s[4:5]
	s_cbranch_vccz .Lscan_nostage
	s_setprio 3
	s_xor_b32 s6, s11, 1
	s_mul_i32 s6, s6, 0x12000
	s_add_i32 s6, s6, s8
	s_mov_b32 s7, m0
	s_add_i32 m0, s6, 0x0
	s_nop 0
	global_load_lds_dwordx4 v[62:63], off
	s_add_i32 m0, s6, 0x2000
	s_nop 0
	global_load_lds_dwordx4 v[64:65], off
	s_add_i32 m0, s6, 0x4000
	s_nop 0
	global_load_lds_dwordx4 v[66:67], off
	s_add_i32 m0, s6, 0x6000
	s_nop 0
	global_load_lds_dwordx4 v[68:69], off
	s_add_i32 m0, s6, 0x8000
	s_nop 0
	global_load_lds_dwordx4 v[70:71], off
	s_add_i32 m0, s6, 0xa000
	s_nop 0
	global_load_lds_dwordx4 v[72:73], off
	s_add_i32 m0, s6, 0xc000
	s_nop 0
	global_load_lds_dwordx4 v[74:75], off
	s_add_i32 m0, s6, 0xe000
	s_nop 0
	global_load_lds_dwordx4 v[76:77], off
	s_add_i32 m0, s6, 0x10000
	s_nop 0
	global_load_lds_dwordx4 v[78:79], off
	s_add_i32 s6, s6, 0xfffff000
	s_add_i32 m0, s6, 0x0
	s_nop 0
	global_load_lds_dwordx4 v[80:81], off
	s_add_i32 m0, s6, 0x2000
	s_nop 0
	global_load_lds_dwordx4 v[82:83], off
	s_add_i32 m0, s6, 0x4000
	s_nop 0
	global_load_lds_dwordx4 v[86:87], off
	s_add_i32 m0, s6, 0x6000
	s_nop 0
	global_load_lds_dwordx4 v[88:89], off
	s_add_i32 m0, s6, 0x8000
	s_nop 0
	global_load_lds_dwordx4 v[90:91], off
	s_add_i32 m0, s6, 0xa000
	s_nop 0
	global_load_lds_dwordx4 v[92:93], off
	s_add_i32 m0, s6, 0xc000
	s_nop 0
	global_load_lds_dwordx4 v[94:95], off
	s_add_i32 m0, s6, 0xe000
	s_nop 0
	global_load_lds_dwordx4 v[96:97], off
	s_add_i32 m0, s6, 0x10000
	s_nop 0
	global_load_lds_dwordx4 v[98:99], off
	s_mov_b32 m0, s7
	s_setprio 0
	s_mov_b64 s[12:13], 0x4000
	s_mov_b64 s[14:15], 0x8000
	v_lshl_add_u64 v[62:63], v[62:63], 0, s[12:13]
	v_lshl_add_u64 v[64:65], v[64:65], 0, s[12:13]
	v_lshl_add_u64 v[66:67], v[66:67], 0, s[12:13]
	v_lshl_add_u64 v[68:69], v[68:69], 0, s[12:13]
	v_lshl_add_u64 v[70:71], v[70:71], 0, s[12:13]
	v_lshl_add_u64 v[72:73], v[72:73], 0, s[12:13]
	v_lshl_add_u64 v[74:75], v[74:75], 0, s[34:35]
	v_lshl_add_u64 v[76:77], v[76:77], 0, s[14:15]
	v_lshl_add_u64 v[78:79], v[78:79], 0, s[14:15]
	v_lshl_add_u64 v[80:81], v[80:81], 0, s[12:13]
	v_lshl_add_u64 v[82:83], v[82:83], 0, s[12:13]
	v_lshl_add_u64 v[86:87], v[86:87], 0, s[12:13]
	v_lshl_add_u64 v[88:89], v[88:89], 0, s[12:13]
	v_lshl_add_u64 v[90:91], v[90:91], 0, s[12:13]
	v_lshl_add_u64 v[92:93], v[92:93], 0, s[12:13]
	v_lshl_add_u64 v[94:95], v[94:95], 0, s[34:35]
	v_lshl_add_u64 v[96:97], v[96:97], 0, s[14:15]
	v_lshl_add_u64 v[98:99], v[98:99], 0, s[14:15]
	s_bitcmp0_b32 s80, 0
	s_cbranch_scc0 .Lscan_nopf
	s_cmp_lt_u32 s10, 62
	s_cbranch_scc0 .Lscan_nopf
	global_load_dword v104, v[62:63], off
	global_load_dword v104, v[64:65], off
	global_load_dword v104, v[66:67], off
	global_load_dword v104, v[68:69], off
	global_load_dword v104, v[70:71], off
	global_load_dword v104, v[72:73], off
	global_load_dword v104, v[74:75], off
	global_load_dword v104, v[76:77], off
	global_load_dword v104, v[78:79], off
	global_load_dword v104, v[80:81], off
	global_load_dword v104, v[82:83], off
	global_load_dword v104, v[86:87], off
	global_load_dword v104, v[88:89], off
	global_load_dword v104, v[90:91], off
	global_load_dword v104, v[92:93], off
	global_load_dword v104, v[94:95], off
	global_load_dword v104, v[96:97], off
	global_load_dword v104, v[98:99], off
.Lscan_nopf:
.Lscan_nostage:
	s_mov_b64 s[6:7], -1
	s_and_b64 vcc, exec, s[4:5]
	s_cbranch_vccz .LBB0_161
	s_bitcmp0_b32 s80, 0
	s_cbranch_scc0 .Lscan_wfull
	s_cmp_lt_u32 s10, 62
	s_cbranch_scc1 .Lscan_w18
.Lscan_wfull:
	s_waitcnt vmcnt(0) lgkmcnt(0)
	s_branch .Lscan_wdone
.Lscan_w18:
	s_waitcnt vmcnt(18) lgkmcnt(0)
.Lscan_wdone:
	s_barrier
	s_mov_b64 s[6:7], 0
